# MLA loop: -mref kept in a 16-register tile used as the C operand of the first QK MFMAs (removes two init MFMAs and two moves per key tile; bitwise identical)
# speedup vs baseline: 1.0093x; 1.0016x over previous
.LBB0_496:
	v_xor_b32_e32 v218, 0x80000000, v127
	v_mov_b32_e32 v219, v218
	v_mov_b32_e32 v220, v218
	v_mov_b32_e32 v221, v218
	v_mov_b32_e32 v222, v218
	v_mov_b32_e32 v223, v218
	v_mov_b32_e32 v224, v218
	v_mov_b32_e32 v225, v218
	v_mov_b32_e32 v226, v218
	v_mov_b32_e32 v227, v218
	v_mov_b32_e32 v228, v218
	v_mov_b32_e32 v229, v218
	v_mov_b32_e32 v230, v218
	v_mov_b32_e32 v231, v218
	v_mov_b32_e32 v232, v218
	v_mov_b32_e32 v233, v218
.Lmla4_top:
	s_add_i32 s17, s15, 2
	s_add_i32 s15, s15, 1
	s_bitcmp1_b32 s15, 0
	s_cselect_b32 s18, 0x6400, 0
	v_add_u32_e32 v126, s18, v123
	v_add_u32_e32 v234, s18, v118
	ds_read_b128 v[148:151], v126
	ds_read_b128 v[152:155], v126 offset:6656
	ds_read_b128 v[156:159], v126 offset:32
	ds_read_b128 v[160:163], v126 offset:6688
	ds_read_b128 v[164:167], v126 offset:64
	ds_read_b128 v[168:171], v126 offset:6720
	ds_read_b128 v[172:175], v126 offset:96
	ds_read_b128 v[176:179], v126 offset:6752
	ds_read_b128 v[180:183], v126 offset:128
	ds_read_b128 v[184:187], v126 offset:6784
	ds_read_b128 v[188:191], v126 offset:160
	ds_read_b128 v[192:195], v126 offset:6816
	s_cmp_lt_u32 s17, s5
	s_cselect_b32 s10, 0, s5
	s_cselect_b32 s11, s59, s14
	s_lshl_b32 s10, s10, 6
	s_sub_i32 s18, s11, s10
	v_add_u32_e32 v236, s18, v125
	v_ashrrev_i32_e32 v237, 31, v236
	v_lshlrev_b64 v[236:237], 10, v[236:237]
	v_lshl_add_u64 v[236:237], v[114:115], 0, v[236:237]
	global_load_dwordx4 v[106:109], v[236:237], off
	global_load_dwordx4 v[102:105], v[236:237], off offset:128
	s_and_saveexec_b64 s[10:11], s[38:39]
	s_cbranch_execz .LBB0_498
	v_add_u32_e32 v236, s18, v124
	v_ashrrev_i32_e32 v237, 31, v236
	v_lshlrev_b64 v[236:237], 6, v[236:237]
	v_lshl_add_u64 v[236:237], v[116:117], 0, v[236:237]
	global_load_dwordx4 v[94:97], v[236:237], off
.LBB0_498:
	s_or_b64 exec, exec, s[10:11]
	s_nop 0
	s_waitcnt lgkmcnt(11)
	v_mfma_f32_32x32x16_bf16 v[34:49], v[148:151], v[74:77], v[218:233]
	s_waitcnt lgkmcnt(10)
	v_mfma_f32_32x32x16_bf16 v[50:65], v[152:155], v[74:77], v[218:233]
	s_waitcnt lgkmcnt(9)
	v_mfma_f32_32x32x16_bf16 v[34:49], v[156:159], v[66:69], v[34:49]
	s_waitcnt lgkmcnt(8)
	v_mfma_f32_32x32x16_bf16 v[50:65], v[160:163], v[66:69], v[50:65]
	s_waitcnt lgkmcnt(7)
	v_mfma_f32_32x32x16_bf16 v[34:49], v[164:167], v[82:85], v[34:49]
	s_waitcnt lgkmcnt(6)
	v_mfma_f32_32x32x16_bf16 v[50:65], v[168:171], v[82:85], v[50:65]
	s_waitcnt lgkmcnt(5)
	v_mfma_f32_32x32x16_bf16 v[34:49], v[172:175], v[70:73], v[34:49]
	s_waitcnt lgkmcnt(4)
	v_mfma_f32_32x32x16_bf16 v[50:65], v[176:179], v[70:73], v[50:65]
	s_waitcnt lgkmcnt(3)
	v_mfma_f32_32x32x16_bf16 v[34:49], v[180:183], v[86:89], v[34:49]
	s_waitcnt lgkmcnt(2)
	v_mfma_f32_32x32x16_bf16 v[50:65], v[184:187], v[86:89], v[50:65]
	s_waitcnt lgkmcnt(1)
	v_mfma_f32_32x32x16_bf16 v[34:49], v[188:191], v[78:81], v[34:49]
	s_waitcnt lgkmcnt(0)
	v_mfma_f32_32x32x16_bf16 v[50:65], v[192:195], v[78:81], v[50:65]
	ds_read_b64_tr_b16 v[196:197], v234 offset:13312
	ds_read_b64_tr_b16 v[198:199], v234 offset:14848
	ds_read_b64_tr_b16 v[200:201], v234 offset:16384
	ds_read_b64_tr_b16 v[202:203], v234 offset:17920
	ds_read_b64_tr_b16 v[204:205], v234 offset:19456
	ds_read_b64_tr_b16 v[206:207], v234 offset:20992
	ds_read_b64_tr_b16 v[214:215], v234 offset:22528
	ds_read_b64_tr_b16 v[216:217], v234 offset:24064
	s_nop 4
	v_max_f32_e32 v126, v35, v35
	v_max_f32_e32 v132, v34, v34
	v_max_f32_e32 v126, v132, v126
	v_max3_f32 v128, v36, v37, v51
	v_max3_f32 v126, v126, v50, v52
	v_max3_f32 v126, v126, v53, v38
	v_max3_f32 v128, v128, v40, v41
	v_max3_f32 v126, v126, v39, v54
	v_max3_f32 v128, v128, v56, v57
	v_max3_f32 v126, v126, v55, v42
	v_max3_f32 v128, v128, v44, v45
	v_max3_f32 v126, v126, v43, v58
	v_max3_f32 v128, v128, v60, v61
	v_max3_f32 v126, v126, v59, v46
	v_max3_f32 v128, v128, v48, v49
	v_max3_f32 v126, v126, v47, v62
	v_max3_f32 v128, v128, v64, v65
	v_max3_f32 v126, v126, v63, v128
	ds_bpermute_b32 v128, v113, v126
	s_waitcnt lgkmcnt(0)
	ds_read_b64_tr_b16 v[148:149], v234 offset:13376
	ds_read_b64_tr_b16 v[150:151], v234 offset:14912
	ds_read_b64_tr_b16 v[152:153], v234 offset:16448
	ds_read_b64_tr_b16 v[154:155], v234 offset:17984
	ds_read_b64_tr_b16 v[156:157], v234 offset:19520
	ds_read_b64_tr_b16 v[158:159], v234 offset:21056
	ds_read_b64_tr_b16 v[160:161], v234 offset:22592
	ds_read_b64_tr_b16 v[162:163], v234 offset:24128
	v_max_f32_e32 v128, v128, v128
	v_max_f32_e32 v126, v126, v128
	v_cmp_lt_f32_e32 vcc, s7, v126
	s_cbranch_vccz .LBB0_502
	v_max_f32_e32 v126, v126, v126
	v_max_f32_e32 v126, 0, v126
	v_add_f32_e32 v126, v127, v126
	v_cvt_pk_bf16_f32 v126, v126, v1
	s_nop 0
	v_lshlrev_b32_e32 v126, 16, v126
	s_and_saveexec_b64 s[10:11], s[36:37]
	s_cbranch_execz .LBB0_501
	v_xor_b32_e32 v128, 0x80000000, v126
	v_cvt_pk_bf16_f32 v128, v128, v1
	s_nop 0
	v_bfi_b32 v98, s2, v128, v98
.LBB0_501:
	s_or_b64 exec, exec, s[10:11]
	v_xor_b32_e32 v218, 0x80000000, v126
	v_mov_b32_e32 v219, v218
	v_mov_b32_e32 v220, v218
	v_mov_b32_e32 v221, v218
	v_mov_b32_e32 v222, v218
	v_mov_b32_e32 v223, v218
	v_mov_b32_e32 v224, v218
	v_mov_b32_e32 v225, v218
	v_mov_b32_e32 v226, v218
	v_mov_b32_e32 v227, v218
	v_mov_b32_e32 v228, v218
	v_mov_b32_e32 v229, v218
	v_mov_b32_e32 v230, v218
	v_mov_b32_e32 v231, v218
	v_mov_b32_e32 v232, v218
	v_mov_b32_e32 v233, v218
	v_sub_f32_e32 v128, v126, v127
	v_exp_f32_e64 v130, -v128
	v_pk_add_f32 v[50:51], v[50:51], v[128:129] op_sel_hi:[1,0] neg_lo:[0,1] neg_hi:[0,1]
	v_pk_add_f32 v[52:53], v[52:53], v[128:129] op_sel_hi:[1,0] neg_lo:[0,1] neg_hi:[0,1]
	v_pk_add_f32 v[54:55], v[54:55], v[128:129] op_sel_hi:[1,0] neg_lo:[0,1] neg_hi:[0,1]
	v_pk_add_f32 v[56:57], v[56:57], v[128:129] op_sel_hi:[1,0] neg_lo:[0,1] neg_hi:[0,1]
	v_pk_add_f32 v[58:59], v[58:59], v[128:129] op_sel_hi:[1,0] neg_lo:[0,1] neg_hi:[0,1]
	v_pk_add_f32 v[60:61], v[60:61], v[128:129] op_sel_hi:[1,0] neg_lo:[0,1] neg_hi:[0,1]
	v_pk_add_f32 v[62:63], v[62:63], v[128:129] op_sel_hi:[1,0] neg_lo:[0,1] neg_hi:[0,1]
	v_pk_add_f32 v[64:65], v[64:65], v[128:129] op_sel_hi:[1,0] neg_lo:[0,1] neg_hi:[0,1]
	v_pk_add_f32 v[34:35], v[34:35], v[128:129] op_sel_hi:[1,0] neg_lo:[0,1] neg_hi:[0,1]
	v_pk_add_f32 v[36:37], v[36:37], v[128:129] op_sel_hi:[1,0] neg_lo:[0,1] neg_hi:[0,1]
	v_pk_add_f32 v[38:39], v[38:39], v[128:129] op_sel_hi:[1,0] neg_lo:[0,1] neg_hi:[0,1]
	v_pk_add_f32 v[40:41], v[40:41], v[128:129] op_sel_hi:[1,0] neg_lo:[0,1] neg_hi:[0,1]
	v_pk_add_f32 v[42:43], v[42:43], v[128:129] op_sel_hi:[1,0] neg_lo:[0,1] neg_hi:[0,1]
	v_pk_add_f32 v[44:45], v[44:45], v[128:129] op_sel_hi:[1,0] neg_lo:[0,1] neg_hi:[0,1]
	v_pk_add_f32 v[46:47], v[46:47], v[128:129] op_sel_hi:[1,0] neg_lo:[0,1] neg_hi:[0,1]
	v_pk_add_f32 v[48:49], v[48:49], v[128:129] op_sel_hi:[1,0] neg_lo:[0,1] neg_hi:[0,1]
	v_pk_mul_f32 v[32:33], v[32:33], v[130:131] op_sel_hi:[1,0]
	v_pk_mul_f32 v[30:31], v[30:31], v[130:131] op_sel_hi:[1,0]
	v_pk_mul_f32 v[28:29], v[28:29], v[130:131] op_sel_hi:[1,0]
	v_pk_mul_f32 v[26:27], v[26:27], v[130:131] op_sel_hi:[1,0]
	v_pk_mul_f32 v[24:25], v[24:25], v[130:131] op_sel_hi:[1,0]
	v_pk_mul_f32 v[22:23], v[22:23], v[130:131] op_sel_hi:[1,0]
	v_pk_mul_f32 v[20:21], v[20:21], v[130:131] op_sel_hi:[1,0]
	v_pk_mul_f32 v[18:19], v[18:19], v[130:131] op_sel_hi:[1,0]
	v_pk_mul_f32 v[16:17], v[16:17], v[130:131] op_sel_hi:[1,0]
	v_pk_mul_f32 v[14:15], v[14:15], v[130:131] op_sel_hi:[1,0]
	v_pk_mul_f32 v[12:13], v[12:13], v[130:131] op_sel_hi:[1,0]
	v_pk_mul_f32 v[10:11], v[10:11], v[130:131] op_sel_hi:[1,0]
	v_pk_mul_f32 v[8:9], v[8:9], v[130:131] op_sel_hi:[1,0]
	v_pk_mul_f32 v[6:7], v[6:7], v[130:131] op_sel_hi:[1,0]
	v_pk_mul_f32 v[4:5], v[4:5], v[130:131] op_sel_hi:[1,0]
	v_pk_mul_f32 v[2:3], v[2:3], v[130:131] op_sel_hi:[1,0]
	v_mul_f32_e32 v119, v119, v130
	s_branch .LBB0_503

.LBB0_503:
	v_exp_f32_e32 v34, v34
	v_exp_f32_e32 v35, v35
	v_exp_f32_e32 v36, v36
	v_exp_f32_e32 v37, v37
	v_exp_f32_e32 v38, v38
	v_exp_f32_e32 v39, v39
	v_exp_f32_e32 v40, v40
	v_exp_f32_e32 v41, v41
	v_cvt_pk_bf16_f32 v128, v34, v35
	v_cvt_pk_bf16_f32 v129, v36, v37
	v_cvt_pk_bf16_f32 v130, v38, v39
	v_cvt_pk_bf16_f32 v131, v40, v41
	v_exp_f32_e32 v42, v42
	v_exp_f32_e32 v43, v43
	v_mfma_f32_32x32x16_bf16 v[2:17], v[196:199], v[128:131], v[2:17]
	s_waitcnt lgkmcnt(6)
	v_mfma_f32_32x32x16_bf16 v[18:33], v[148:151], v[128:131], v[18:33]
	v_exp_f32_e32 v44, v44
	v_exp_f32_e32 v45, v45
	v_exp_f32_e32 v46, v46
	v_exp_f32_e32 v47, v47
	v_exp_f32_e32 v48, v48
	v_exp_f32_e32 v49, v49
	v_cvt_pk_bf16_f32 v136, v42, v43
	v_cvt_pk_bf16_f32 v137, v44, v45
	v_cvt_pk_bf16_f32 v138, v46, v47
	v_cvt_pk_bf16_f32 v139, v48, v49
	v_exp_f32_e32 v50, v50
	v_exp_f32_e32 v51, v51
	v_mfma_f32_32x32x16_bf16 v[2:17], v[200:203], v[136:139], v[2:17]
	s_waitcnt lgkmcnt(4)
	v_mfma_f32_32x32x16_bf16 v[18:33], v[152:155], v[136:139], v[18:33]
	v_exp_f32_e32 v52, v52
	v_exp_f32_e32 v53, v53
	v_exp_f32_e32 v54, v54
	v_exp_f32_e32 v55, v55
	v_exp_f32_e32 v56, v56
	v_exp_f32_e32 v57, v57
	v_cvt_pk_bf16_f32 v132, v50, v51
	v_cvt_pk_bf16_f32 v133, v52, v53
	v_cvt_pk_bf16_f32 v134, v54, v55
	v_cvt_pk_bf16_f32 v135, v56, v57
	v_exp_f32_e32 v58, v58
	v_exp_f32_e32 v59, v59
	v_mfma_f32_32x32x16_bf16 v[2:17], v[204:207], v[132:135], v[2:17]
	s_waitcnt lgkmcnt(2)
	v_mfma_f32_32x32x16_bf16 v[18:33], v[156:159], v[132:135], v[18:33]
	v_exp_f32_e32 v60, v60
	v_exp_f32_e32 v61, v61
	v_exp_f32_e32 v62, v62
	v_exp_f32_e32 v63, v63
	v_exp_f32_e32 v64, v64
	v_exp_f32_e32 v65, v65
	v_cvt_pk_bf16_f32 v140, v58, v59
	v_cvt_pk_bf16_f32 v141, v60, v61
	v_cvt_pk_bf16_f32 v142, v62, v63
	v_cvt_pk_bf16_f32 v143, v64, v65
	s_bitcmp1_b32 s17, 0
	s_cselect_b32 s10, 0x6400, 0
	s_add_i32 s17, s10, 0
	v_mfma_f32_32x32x16_bf16 v[2:17], v[214:217], v[140:143], v[2:17]
	s_waitcnt lgkmcnt(0)
	v_mfma_f32_32x32x16_bf16 v[18:33], v[160:163], v[140:143], v[18:33]
	v_add_u32_e32 v238, s17, v120
	v_add_u32_e32 v239, s17, v121
	s_waitcnt vmcnt(1)
	ds_write_b128 v238, v[106:109]
	s_waitcnt vmcnt(0)
	ds_write_b128 v239, v[102:105] offset:13312
	s_and_saveexec_b64 s[10:11], s[38:39]
	v_add3_u32 v238, s17, v112, v122
	ds_write_b128 v238, v[94:97] offset:128
	s_or_b64 exec, exec, s[10:11]
	v_add_f32_e32 v34, v50, v34
	v_add_f32_e32 v35, v51, v35
	v_add_f32_e32 v34, 0, v34
	v_add_f32_e32 v36, v52, v36
	v_add_f32_e32 v34, v35, v34
	v_add_f32_e32 v37, v53, v37
	v_add_f32_e32 v34, v36, v34
	v_add_f32_e32 v38, v54, v38
	v_add_f32_e32 v34, v37, v34
	v_add_f32_e32 v39, v55, v39
	v_add_f32_e32 v34, v38, v34
	v_add_f32_e32 v40, v56, v40
	v_add_f32_e32 v34, v39, v34
	v_add_f32_e32 v41, v57, v41
	v_add_f32_e32 v34, v40, v34
	v_add_f32_e32 v42, v58, v42
	v_add_f32_e32 v34, v41, v34
	v_add_f32_e32 v43, v59, v43
	v_add_f32_e32 v34, v42, v34
	v_add_f32_e32 v44, v60, v44
	v_add_f32_e32 v34, v43, v34
	v_add_f32_e32 v45, v61, v45
	v_add_f32_e32 v34, v44, v34
	v_add_f32_e32 v46, v62, v46
	v_add_f32_e32 v34, v45, v34
	v_add_f32_e32 v47, v63, v47
	v_add_f32_e32 v34, v46, v34
	v_add_f32_e32 v48, v64, v48
	v_add_f32_e32 v34, v47, v34
	v_add_f32_e32 v49, v65, v49
	v_add_f32_e32 v34, v48, v34
	v_add_f32_e32 v34, v49, v34
	v_add_f32_e32 v119, v119, v34
	v_add_u32_e32 v124, 64, v124
	s_cmp_lg_u32 s16, s15
	v_add_u32_e32 v125, 64, v125
	s_waitcnt lgkmcnt(0)
	s_barrier
	s_cbranch_scc0 .LBB0_507
	v_mov_b32_e32 v127, v126
	s_branch .Lmla4_top
